# P5 out-epilogue: res_gate vector loaded once per tile into spare VGPRs, per-store reload + vmcnt(0) drain removed (on top of norm/final rewrite)
# speedup vs baseline: 1.0299x; 1.0299x over previous
; #define LAS __attribute__((address_space(3)))
;     __device__ __forceinline__ void operator()(const f32x4 (&acc)[2][2][4][2], const UnitD& u, int wr, int wc, int lane, LAS unsigned char* eb) const {
;     ...
;             f32x4 xr[4][2][2];
; #pragma unroll
;             for (int m = 0; m < 4; ++m)
; #pragma unroll
;                 for (int bj = 0; bj < 2; ++bj)
; #pragma unroll
;                     for (int hf = 0; hf < 2; ++hf) { const int r = 8 * hf + rr, c = cl ^ (r & 7);
;                         xr[m][bj][hf] = *(const f32x4*)(xres + (size_t)(u.pm * BM + ai * HALF + wr * 64 + m * 16 + r) * DM + colw + 32 * bj + 4 * c); }
; #pragma unroll
;             for (int m = 0; m < 4; ++m)
; #pragma unroll
;                 for (int bj = 0; bj < 2; ++bj) {
; #pragma unroll
;                     for (int n = 0; n < 2; ++n) *(LAS f32x4*)(eb + epi_wr_off(fr, 2 * fq + n)) = acc[ai][bj][m][n];
; #pragma unroll
;                     for (int hf = 0; hf < 2; ++hf) { const int r = 8 * hf + rr, c = cl ^ (r & 7); const int col = colw + 32 * bj + 4 * c;
;                         const f32x4 av = *(const LAS f32x4*)(eb + r * 128 + cl * 16);
;                         const f32x4 rgv = *(const f32x4*)(rg + (size_t)b * NMOD + col);
;                         *(f32x4*)(out + (size_t)(u.pm * BM + ai * HALF + wr * 64 + m * 16 + r) * DM + col) = xr[m][bj][hf] + rgv * av; }
.LBB0_603:
	s_ashr_i32 s13, s33, 31
	v_mov_b32_e32 v132, v164
	s_lshr_b32 s13, s13, 28
	s_add_i32 s13, s33, s13
	v_ashrrev_i32_e32 v167, 3, v132
	s_ashr_i32 s15, s13, 4
	s_lshl_b32 s13, s45, 8
	v_xor_b32_e32 v128, v167, v132
	s_or_b32 s20, s13, s43
	v_lshlrev_b32_e32 v128, 2, v128
	s_lshl_b32 s13, s33, 8
	s_ashr_i32 s21, s20, 31
	v_and_b32_e32 v129, 28, v128
	s_add_i32 s13, s13, s39
	v_or_b32_e32 v128, s20, v129
	s_lshl_b64 s[20:21], s[20:21], 2
	s_add_u32 s20, s8, s20
	v_add_u32_e32 v160, s13, v167
	s_mul_hi_i32 s22, s15, 0x6000
	s_mulk_i32 s15, 0x6000
	s_addc_u32 s21, s9, s21
	v_lshlrev_b32_e32 v194, 2, v129
	v_lshl_add_u64 v[162:163], s[20:21], 0, v[194:195]
	v_ashrrev_i32_e32 v161, 31, v160
	v_ashrrev_i32_e32 v129, 31, v128
	s_add_u32 s20, s37, s15
	v_lshlrev_b64 v[196:197], 13, v[160:161]
	s_addc_u32 s21, s38, s22
	v_lshlrev_b64 v[158:159], 2, v[128:129]
	v_lshl_add_u64 v[130:131], v[162:163], 0, v[196:197]
	v_lshl_add_u64 v[156:157], s[20:21], 0, v[158:159]
	global_load_dwordx4 v[170:173], v[130:131], off
	global_load_dwordx4 v[174:177], v[156:157], off
	global_load_dwordx2 v[232:233], v[156:157], off
	global_load_dword v231, v[156:157], off offset:8
	global_load_dword v237, v[156:157], off offset:12
	global_load_dwordx2 v[248:249], v[156:157], off offset:128
	global_load_dword v247, v[156:157], off offset:136
	global_load_dword v238, v[156:157], off offset:140
	v_lshlrev_b32_e32 v128, 7, v132
	v_and_b32_e32 v128, 0x780, v128
	v_add_u32_e32 v135, s42, v128
	v_lshlrev_b32_e32 v128, 4, v132
	v_and_b32_e32 v128, 0x70, v128
	v_add_u32_e32 v194, s42, v128
	v_add_u32_e32 v128, 8, v160
	v_ashrrev_i32_e32 v129, 31, v128
	v_lshlrev_b64 v[128:129], 13, v[128:129]
	v_lshl_add_u64 v[128:129], v[162:163], 0, v[128:129]
	global_load_dwordx4 v[178:181], v[130:131], off offset:128
	global_load_dwordx4 v[182:185], v[128:129], off
	global_load_dwordx4 v[186:189], v[128:129], off offset:128
	v_add_u32_e32 v128, 16, v160
	v_add_u32_e32 v130, 24, v160
	v_ashrrev_i32_e32 v129, 31, v128
	v_ashrrev_i32_e32 v131, 31, v130
	v_lshlrev_b64 v[128:129], 13, v[128:129]
	v_lshlrev_b64 v[130:131], 13, v[130:131]
	v_lshl_add_u64 v[128:129], v[162:163], 0, v[128:129]
	v_lshl_add_u64 v[130:131], v[162:163], 0, v[130:131]
	global_load_dwordx4 v[190:193], v[128:129], off
	global_load_dwordx4 v[200:203], v[128:129], off offset:128
	global_load_dwordx4 v[204:207], v[130:131], off
	global_load_dwordx4 v[208:211], v[130:131], off offset:128
	v_add_u32_e32 v128, 32, v160
	v_add_u32_e32 v130, 40, v160
	v_ashrrev_i32_e32 v129, 31, v128
	v_ashrrev_i32_e32 v131, 31, v130
	v_lshlrev_b64 v[128:129], 13, v[128:129]
	v_lshlrev_b64 v[130:131], 13, v[130:131]
	v_lshl_add_u64 v[128:129], v[162:163], 0, v[128:129]
	v_lshl_add_u64 v[130:131], v[162:163], 0, v[130:131]
	global_load_dwordx4 v[212:215], v[128:129], off
	global_load_dwordx4 v[140:143], v[128:129], off offset:128
	global_load_dwordx4 v[216:219], v[130:131], off
	global_load_dwordx4 v[136:139], v[130:131], off offset:128
	v_add_u32_e32 v130, 56, v160
	v_ashrrev_i32_e32 v131, 31, v130
	v_and_b32_e32 v134, 7, v132
	v_lshlrev_b64 v[130:131], 13, v[130:131]
	s_mov_b32 s15, 0xffffffe
	v_lshl_add_u64 v[198:199], v[162:163], 0, v[130:131]
	v_bitop3_b32 v130, v167, v134, s15 bitop3:0x6c
	v_and_b32_e32 v133, 0xffffffe, v167
	v_lshl_add_u32 v168, v130, 4, v135
	ds_write_b128 v168, v[124:127]
	v_bitop3_b32 v124, v133, v134, 1 bitop3:0x36
	v_lshl_add_u32 v169, v124, 4, v135
	v_lshl_add_u32 v161, v167, 7, v194
	ds_write_b128 v169, v[120:123]
	ds_read_b128 v[220:223], v161
	v_add_u32_e32 v128, 48, v160
	v_ashrrev_i32_e32 v129, 31, v128
	v_lshlrev_b64 v[128:129], 13, v[128:129]
	v_lshl_add_u64 v[128:129], v[162:163], 0, v[128:129]
	global_load_dwordx4 v[132:135], v[128:129], off
	global_load_dwordx4 v[124:127], v[128:129], off offset:128
	s_nop 0
	global_load_dwordx4 v[128:131], v[198:199], off
	global_load_dwordx4 v[120:123], v[198:199], off offset:128
	s_or_b32 s15, s13, 16
	s_andn2_b64 vcc, exec, s[2:3]
	s_mov_b64 s[2:3], -1
	s_waitcnt vmcnt(0) lgkmcnt(0)
	v_pk_fma_f32 v[170:171], v[220:221], v[174:175], v[170:171]
	v_lshl_add_u64 v[174:175], s[4:5], 0, v[196:197]
	v_pk_fma_f32 v[172:173], v[222:223], v[176:177], v[172:173]
	v_lshl_add_u64 v[176:177], v[174:175], 0, v[158:159]
	global_store_dwordx4 v[176:177], v[170:173], off
	s_nop 1
	v_mov_b32_e32 v172, v232
	v_mov_b32_e32 v173, v233
	v_mov_b32_e32 v174, v231
	v_mov_b32_e32 v175, v237
	s_nop 0
	v_add_u32_e32 v171, 8, v167
	v_lshl_add_u32 v170, v171, 7, v194
	ds_read_b128 v[220:223], v170
	v_add_u32_e32 v196, s13, v171
	v_ashrrev_i32_e32 v197, 31, v196
	v_lshlrev_b64 v[196:197], 13, v[196:197]
	v_lshl_add_u64 v[196:197], s[4:5], 0, v[196:197]
	v_lshl_add_u64 v[196:197], v[196:197], 0, v[158:159]
	s_waitcnt lgkmcnt(0)
	v_pk_fma_f32 v[174:175], v[222:223], v[174:175], v[184:185]
	v_pk_fma_f32 v[172:173], v[220:221], v[172:173], v[182:183]
	global_store_dwordx4 v[196:197], v[172:175], off
	s_nop 1
	v_mov_b32_e32 v172, v248
	v_mov_b32_e32 v173, v249
	v_mov_b32_e32 v174, v247
	v_mov_b32_e32 v175, v238
	ds_write_b128 v168, v[116:119]
	ds_write_b128 v169, v[112:115]
	ds_read_b128 v[112:115], v161
	ds_read_b128 v[116:119], v170
	s_waitcnt lgkmcnt(1)
	v_pk_fma_f32 v[114:115], v[114:115], v[174:175], v[180:181]
	v_pk_fma_f32 v[112:113], v[112:113], v[172:173], v[178:179]
	global_store_dwordx4 v[176:177], v[112:115], off offset:128
	s_nop 1
	v_mov_b32_e32 v112, v248
	v_mov_b32_e32 v113, v249
	v_mov_b32_e32 v114, v247
	v_mov_b32_e32 v115, v238
	s_waitcnt lgkmcnt(0)
; #define LAS __attribute__((address_space(3)))
;     __device__ __forceinline__ void operator()(const f32x4 (&acc)[2][2][4][2], const UnitD& u, int wr, int wc, int lane, LAS unsigned char* eb) const {
;     ...
;             for (int m = 0; m < 4; ++m)
; #pragma unroll
;                 for (int bj = 0; bj < 2; ++bj) {
; #pragma unroll
;                     for (int n = 0; n < 2; ++n) *(LAS f32x4*)(eb + epi_wr_off(fr, 2 * fq + n)) = acc[ai][bj][m][n];
; #pragma unroll
;                     for (int hf = 0; hf < 2; ++hf) { const int r = 8 * hf + rr, c = cl ^ (r & 7); const int col = colw + 32 * bj + 4 * c;
;                         const f32x4 av = *(const LAS f32x4*)(eb + r * 128 + cl * 16);
;                         const f32x4 rgv = *(const f32x4*)(rg + (size_t)b * NMOD + col);
;                         *(f32x4*)(out + (size_t)(u.pm * BM + ai * HALF + wr * 64 + m * 16 + r) * DM + col) = xr[m][bj][hf] + rgv * av; }
	v_pk_fma_f32 v[114:115], v[118:119], v[114:115], v[188:189]
	v_pk_fma_f32 v[112:113], v[116:117], v[112:113], v[186:187]
	global_store_dwordx4 v[196:197], v[112:115], off offset:128
	s_nop 1
	v_mov_b32_e32 v112, v232
	v_mov_b32_e32 v113, v233
	v_mov_b32_e32 v114, v231
	v_mov_b32_e32 v115, v237
	ds_write_b128 v168, v[108:111]
	ds_write_b128 v169, v[104:107]
	ds_read_b128 v[104:107], v161
	v_add_u32_e32 v108, s15, v167
	v_ashrrev_i32_e32 v109, 31, v108
	v_lshlrev_b64 v[108:109], 13, v[108:109]
	v_lshl_add_u64 v[108:109], s[4:5], 0, v[108:109]
	v_lshl_add_u64 v[116:117], v[108:109], 0, v[158:159]
	ds_read_b128 v[108:111], v170
	s_waitcnt lgkmcnt(1)
	v_pk_fma_f32 v[106:107], v[106:107], v[114:115], v[192:193]
	v_pk_fma_f32 v[104:105], v[104:105], v[112:113], v[190:191]
	global_store_dwordx4 v[116:117], v[104:107], off
	s_nop 1
	v_mov_b32_e32 v104, v232
	v_mov_b32_e32 v105, v233
	v_mov_b32_e32 v106, v231
	v_mov_b32_e32 v107, v237
	v_add_u32_e32 v112, s15, v171
	v_ashrrev_i32_e32 v113, 31, v112
	v_lshlrev_b64 v[112:113], 13, v[112:113]
	v_lshl_add_u64 v[112:113], s[4:5], 0, v[112:113]
	v_lshl_add_u64 v[112:113], v[112:113], 0, v[158:159]
	s_or_b32 s15, s13, 32
	s_waitcnt lgkmcnt(0)
	v_pk_fma_f32 v[106:107], v[110:111], v[106:107], v[206:207]
	v_pk_fma_f32 v[104:105], v[108:109], v[104:105], v[204:205]
	global_store_dwordx4 v[112:113], v[104:107], off
	s_nop 1
	v_mov_b32_e32 v104, v248
	v_mov_b32_e32 v105, v249
	v_mov_b32_e32 v106, v247
	v_mov_b32_e32 v107, v238
	ds_write_b128 v168, v[100:103]
	ds_write_b128 v169, v[96:99]
	ds_read_b128 v[96:99], v161
	ds_read_b128 v[100:103], v170
	s_waitcnt lgkmcnt(1)
	v_pk_fma_f32 v[98:99], v[98:99], v[106:107], v[202:203]
	v_pk_fma_f32 v[96:97], v[96:97], v[104:105], v[200:201]
	global_store_dwordx4 v[116:117], v[96:99], off offset:128
	s_nop 1
	v_mov_b32_e32 v96, v248
	v_mov_b32_e32 v97, v249
	v_mov_b32_e32 v98, v247
	v_mov_b32_e32 v99, v238
	s_waitcnt lgkmcnt(0)
	v_pk_fma_f32 v[98:99], v[102:103], v[98:99], v[210:211]
	v_pk_fma_f32 v[96:97], v[100:101], v[96:97], v[208:209]
	global_store_dwordx4 v[112:113], v[96:99], off offset:128
	s_nop 1
	v_mov_b32_e32 v96, v232
	v_mov_b32_e32 v97, v233
	v_mov_b32_e32 v98, v231
	v_mov_b32_e32 v99, v237
	ds_write_b128 v168, v[92:95]
	ds_write_b128 v169, v[88:91]
	ds_read_b128 v[88:91], v161
	v_add_u32_e32 v100, s15, v167
	v_ashrrev_i32_e32 v101, 31, v100
	v_lshlrev_b64 v[92:93], 13, v[100:101]
	v_lshl_add_u64 v[92:93], s[4:5], 0, v[92:93]
	v_lshl_add_u64 v[100:101], v[92:93], 0, v[158:159]
	ds_read_b128 v[92:95], v170
	s_waitcnt lgkmcnt(1)
	v_pk_fma_f32 v[90:91], v[90:91], v[98:99], v[214:215]
	v_pk_fma_f32 v[88:89], v[88:89], v[96:97], v[212:213]
	global_store_dwordx4 v[100:101], v[88:91], off
	s_nop 1
	v_mov_b32_e32 v88, v232
	v_mov_b32_e32 v89, v233
	v_mov_b32_e32 v90, v231
	v_mov_b32_e32 v91, v237
	v_add_u32_e32 v96, s15, v171
	v_ashrrev_i32_e32 v97, 31, v96
	v_lshlrev_b64 v[96:97], 13, v[96:97]
	v_lshl_add_u64 v[96:97], s[4:5], 0, v[96:97]
	v_lshl_add_u64 v[96:97], v[96:97], 0, v[158:159]
	s_or_b32 s15, s13, 48
	s_waitcnt lgkmcnt(0)
	v_pk_fma_f32 v[90:91], v[94:95], v[90:91], v[218:219]
	v_pk_fma_f32 v[88:89], v[92:93], v[88:89], v[216:217]
	global_store_dwordx4 v[96:97], v[88:91], off
	s_nop 1
	v_mov_b32_e32 v88, v248
	v_mov_b32_e32 v89, v249
	v_mov_b32_e32 v90, v247
	v_mov_b32_e32 v91, v238
	ds_write_b128 v168, v[84:87]
	ds_write_b128 v169, v[80:83]
	ds_read_b128 v[80:83], v161
	ds_read_b128 v[84:87], v170
	s_waitcnt lgkmcnt(1)
	v_pk_fma_f32 v[82:83], v[82:83], v[90:91], v[142:143]
	v_pk_fma_f32 v[80:81], v[80:81], v[88:89], v[140:141]
	global_store_dwordx4 v[100:101], v[80:83], off offset:128
	s_nop 1
	v_mov_b32_e32 v80, v248
	v_mov_b32_e32 v81, v249
	v_mov_b32_e32 v82, v247
	v_mov_b32_e32 v83, v238
	s_waitcnt lgkmcnt(0)
	v_pk_fma_f32 v[82:83], v[86:87], v[82:83], v[138:139]
	v_pk_fma_f32 v[80:81], v[84:85], v[80:81], v[136:137]
	global_store_dwordx4 v[96:97], v[80:83], off offset:128
	s_nop 1
	v_mov_b32_e32 v80, v232
	v_mov_b32_e32 v81, v233
	v_mov_b32_e32 v82, v231
	v_mov_b32_e32 v83, v237
	ds_write_b128 v168, v[76:79]
	ds_write_b128 v169, v[72:75]
	ds_read_b128 v[72:75], v161
	v_add_u32_e32 v84, s15, v167
	v_ashrrev_i32_e32 v85, 31, v84
	v_lshlrev_b64 v[76:77], 13, v[84:85]
	v_lshl_add_u64 v[76:77], s[4:5], 0, v[76:77]
	v_lshl_add_u64 v[84:85], v[76:77], 0, v[158:159]
	ds_read_b128 v[76:79], v170
	v_add_u32_e32 v86, 0xb8, v160
	v_ashrrev_i32_e32 v87, 31, v86
	v_lshlrev_b64 v[86:87], 13, v[86:87]
	s_waitcnt lgkmcnt(1)
	v_pk_fma_f32 v[74:75], v[74:75], v[82:83], v[134:135]
	v_pk_fma_f32 v[72:73], v[72:73], v[80:81], v[132:133]
	global_store_dwordx4 v[84:85], v[72:75], off
	s_nop 1
	v_mov_b32_e32 v72, v232
	v_mov_b32_e32 v73, v233
	v_mov_b32_e32 v74, v231
	v_mov_b32_e32 v75, v237
	v_add_u32_e32 v80, s15, v171
	v_ashrrev_i32_e32 v81, 31, v80
	v_lshlrev_b64 v[80:81], 13, v[80:81]
	v_lshl_add_u64 v[80:81], s[4:5], 0, v[80:81]
	v_lshl_add_u64 v[80:81], v[80:81], 0, v[158:159]
	s_add_i32 s15, s13, 0x80
	s_waitcnt lgkmcnt(0)
	v_pk_fma_f32 v[74:75], v[78:79], v[74:75], v[130:131]
	v_pk_fma_f32 v[72:73], v[76:77], v[72:73], v[128:129]
	global_store_dwordx4 v[80:81], v[72:75], off
	s_nop 1
	v_mov_b32_e32 v72, v248
	v_mov_b32_e32 v73, v249
	v_mov_b32_e32 v74, v247
	v_mov_b32_e32 v75, v238
	ds_write_b128 v168, v[68:71]
	ds_write_b128 v169, v[64:67]
	ds_read_b128 v[64:67], v161
	ds_read_b128 v[68:71], v170
	v_lshl_add_u64 v[130:131], v[162:163], 0, v[86:87]
	s_waitcnt lgkmcnt(1)
; #define LAS __attribute__((address_space(3)))
;     __device__ __forceinline__ void operator()(const f32x4 (&acc)[2][2][4][2], const UnitD& u, int wr, int wc, int lane, LAS unsigned char* eb) const {
;     ...
;             f32x4 xr[4][2][2];
; #pragma unroll
;             for (int m = 0; m < 4; ++m)
; #pragma unroll
;                 for (int bj = 0; bj < 2; ++bj)
; #pragma unroll
;                     for (int hf = 0; hf < 2; ++hf) { const int r = 8 * hf + rr, c = cl ^ (r & 7);
;                         xr[m][bj][hf] = *(const f32x4*)(xres + (size_t)(u.pm * BM + ai * HALF + wr * 64 + m * 16 + r) * DM + colw + 32 * bj + 4 * c); }
; #pragma unroll
;             for (int m = 0; m < 4; ++m)
; #pragma unroll
;                 for (int bj = 0; bj < 2; ++bj) {
; #pragma unroll
;                     for (int n = 0; n < 2; ++n) *(LAS f32x4*)(eb + epi_wr_off(fr, 2 * fq + n)) = acc[ai][bj][m][n];
; #pragma unroll
;                     for (int hf = 0; hf < 2; ++hf) { const int r = 8 * hf + rr, c = cl ^ (r & 7); const int col = colw + 32 * bj + 4 * c;
;                         const f32x4 av = *(const LAS f32x4*)(eb + r * 128 + cl * 16);
;                         const f32x4 rgv = *(const f32x4*)(rg + (size_t)b * NMOD + col);
;                         *(f32x4*)(out + (size_t)(u.pm * BM + ai * HALF + wr * 64 + m * 16 + r) * DM + col) = xr[m][bj][hf] + rgv * av; }
	v_pk_fma_f32 v[66:67], v[66:67], v[74:75], v[126:127]
	v_pk_fma_f32 v[64:65], v[64:65], v[72:73], v[124:125]
	global_store_dwordx4 v[84:85], v[64:67], off offset:128
	s_nop 1
	v_mov_b32_e32 v64, v248
	v_mov_b32_e32 v65, v249
	v_mov_b32_e32 v66, v247
	v_mov_b32_e32 v67, v238
	v_add_u32_e32 v72, 0x80, v160
	v_ashrrev_i32_e32 v73, 31, v72
	v_lshlrev_b64 v[72:73], 13, v[72:73]
	v_lshl_add_u64 v[82:83], v[162:163], 0, v[72:73]
	v_add_u32_e32 v84, 0xb0, v160
	v_ashrrev_i32_e32 v85, 31, v84
	v_lshlrev_b64 v[84:85], 13, v[84:85]
	v_lshl_add_u64 v[128:129], v[162:163], 0, v[84:85]
	s_waitcnt lgkmcnt(0)
	v_pk_fma_f32 v[66:67], v[70:71], v[66:67], v[122:123]
	v_pk_fma_f32 v[64:65], v[68:69], v[64:65], v[120:121]
	global_store_dwordx4 v[80:81], v[64:67], off offset:128
	global_load_dwordx4 v[72:75], v[82:83], off
	s_nop 1
	v_mov_b32_e32 v76, v232
	v_mov_b32_e32 v77, v233
	v_mov_b32_e32 v78, v231
	v_mov_b32_e32 v79, v237
	v_add_u32_e32 v80, 0xa8, v160
	v_ashrrev_i32_e32 v81, 31, v80
	v_lshlrev_b64 v[80:81], 13, v[80:81]
	v_lshl_add_u64 v[120:121], v[162:163], 0, v[80:81]
	v_add_u32_e32 v80, s15, v167
	v_add_u32_e32 v64, 0x88, v160
	v_add_u32_e32 v66, 0x90, v160
	v_add_u32_e32 v68, 0x98, v160
	v_add_u32_e32 v70, 0xa0, v160
	v_ashrrev_i32_e32 v81, 31, v80
	v_ashrrev_i32_e32 v65, 31, v64
	v_ashrrev_i32_e32 v67, 31, v66
	v_ashrrev_i32_e32 v69, 31, v68
	v_ashrrev_i32_e32 v71, 31, v70
	v_lshlrev_b64 v[80:81], 13, v[80:81]
	v_lshlrev_b64 v[64:65], 13, v[64:65]
	v_lshlrev_b64 v[66:67], 13, v[66:67]
	v_lshlrev_b64 v[68:69], 13, v[68:69]
	v_lshlrev_b64 v[70:71], 13, v[70:71]
	v_lshl_add_u64 v[80:81], s[4:5], 0, v[80:81]
	ds_write_b128 v168, v[60:63]
	ds_write_b128 v169, v[56:59]
	v_lshl_add_u64 v[64:65], v[162:163], 0, v[64:65]
	v_lshl_add_u64 v[66:67], v[162:163], 0, v[66:67]
	v_lshl_add_u64 v[68:69], v[162:163], 0, v[68:69]
	v_lshl_add_u64 v[70:71], v[162:163], 0, v[70:71]
	v_lshl_add_u64 v[132:133], v[80:81], 0, v[158:159]
	global_load_dwordx4 v[80:83], v[82:83], off offset:128
	s_nop 0
	global_load_dwordx4 v[84:87], v[64:65], off
	global_load_dwordx4 v[88:91], v[64:65], off offset:128
	global_load_dwordx4 v[92:95], v[66:67], off
	global_load_dwordx4 v[96:99], v[66:67], off offset:128
	global_load_dwordx4 v[100:103], v[68:69], off
	global_load_dwordx4 v[104:107], v[68:69], off offset:128
	global_load_dwordx4 v[108:111], v[70:71], off
	global_load_dwordx4 v[112:115], v[70:71], off offset:128
	global_load_dwordx4 v[116:119], v[120:121], off
	s_nop 0
	global_load_dwordx4 v[120:123], v[120:121], off offset:128
	ds_read_b128 v[124:127], v161
	global_load_dwordx4 v[68:71], v[128:129], off
	global_load_dwordx4 v[60:63], v[128:129], off offset:128
	global_load_dwordx4 v[64:67], v[130:131], off
	global_load_dwordx4 v[56:59], v[130:131], off offset:128
	s_waitcnt vmcnt(15) lgkmcnt(0)
	v_pk_fma_f32 v[74:75], v[126:127], v[78:79], v[74:75]
	v_pk_fma_f32 v[72:73], v[124:125], v[76:77], v[72:73]
	global_store_dwordx4 v[132:133], v[72:75], off
	s_nop 1
	v_mov_b32_e32 v72, v232
	v_mov_b32_e32 v73, v233
	v_mov_b32_e32 v74, v231
	v_mov_b32_e32 v75, v237
	ds_read_b128 v[76:79], v170
	v_add_u32_e32 v124, s15, v171
	v_ashrrev_i32_e32 v125, 31, v124
	v_lshlrev_b64 v[124:125], 13, v[124:125]
	v_lshl_add_u64 v[124:125], s[4:5], 0, v[124:125]
	v_lshl_add_u64 v[124:125], v[124:125], 0, v[158:159]
	s_add_i32 s15, s13, 0x90
	s_waitcnt vmcnt(0) lgkmcnt(0)
	v_pk_fma_f32 v[74:75], v[78:79], v[74:75], v[86:87]
	v_pk_fma_f32 v[72:73], v[76:77], v[72:73], v[84:85]
	global_store_dwordx4 v[124:125], v[72:75], off
	s_nop 1
	v_mov_b32_e32 v72, v248
	v_mov_b32_e32 v73, v249
	v_mov_b32_e32 v74, v247
	v_mov_b32_e32 v75, v238
	ds_write_b128 v168, v[52:55]
	ds_write_b128 v169, v[48:51]
	ds_read_b128 v[48:51], v161
	ds_read_b128 v[52:55], v170
	s_waitcnt lgkmcnt(1)
	v_pk_fma_f32 v[50:51], v[50:51], v[74:75], v[82:83]
	v_pk_fma_f32 v[48:49], v[48:49], v[72:73], v[80:81]
	global_store_dwordx4 v[132:133], v[48:51], off offset:128
	s_nop 1
	v_mov_b32_e32 v48, v248
	v_mov_b32_e32 v49, v249
	v_mov_b32_e32 v50, v247
	v_mov_b32_e32 v51, v238
	s_waitcnt lgkmcnt(0)
	v_pk_fma_f32 v[50:51], v[54:55], v[50:51], v[90:91]
	v_pk_fma_f32 v[48:49], v[52:53], v[48:49], v[88:89]
	global_store_dwordx4 v[124:125], v[48:51], off offset:128
	s_nop 1
	v_mov_b32_e32 v48, v232
	v_mov_b32_e32 v49, v233
	v_mov_b32_e32 v50, v231
	v_mov_b32_e32 v51, v237
	ds_write_b128 v168, v[44:47]
	ds_write_b128 v169, v[40:43]
	ds_read_b128 v[40:43], v161
	v_add_u32_e32 v52, s15, v167
	v_ashrrev_i32_e32 v53, 31, v52
	v_lshlrev_b64 v[44:45], 13, v[52:53]
	v_lshl_add_u64 v[44:45], s[4:5], 0, v[44:45]
	v_lshl_add_u64 v[52:53], v[44:45], 0, v[158:159]
	ds_read_b128 v[44:47], v170
	s_waitcnt lgkmcnt(1)
; #define LAS __attribute__((address_space(3)))
; #define PG8_BAR __builtin_amdgcn_s_barrier()
;     __device__ __forceinline__ void operator()(const f32x4 (&acc)[2][2][4][2], const UnitD& u, int wr, int wc, int lane, LAS unsigned char* eb) const {
;     ...
;             for (int m = 0; m < 4; ++m)
; #pragma unroll
;                 for (int bj = 0; bj < 2; ++bj) {
; #pragma unroll
;                     for (int n = 0; n < 2; ++n) *(LAS f32x4*)(eb + epi_wr_off(fr, 2 * fq + n)) = acc[ai][bj][m][n];
; #pragma unroll
;                     for (int hf = 0; hf < 2; ++hf) { const int r = 8 * hf + rr, c = cl ^ (r & 7); const int col = colw + 32 * bj + 4 * c;
;                         const f32x4 av = *(const LAS f32x4*)(eb + r * 128 + cl * 16);
;                         const f32x4 rgv = *(const f32x4*)(rg + (size_t)b * NMOD + col);
;                         *(f32x4*)(out + (size_t)(u.pm * BM + ai * HALF + wr * 64 + m * 16 + r) * DM + col) = xr[m][bj][hf] + rgv * av; }
; template <class Epi, class Sched>
; __device__ __forceinline__ void gemm_stream(LAS unsigned char* lds, const int lda, const int ldb, const Sched& S, const Epi& E, const int wv) {
;     ...
;         if (!has_next) break;
; #pragma unroll
;         for (int a = 0; a < 2; ++a)
; #pragma unroll
;             for (int b = 0; b < 2; ++b)
; #pragma unroll
;                 for (int m = 0; m < 4; ++m)
; #pragma unroll
;                     for (int n = 0; n < 2; ++n) acc[a][b][m][n] = (f32x4){0.f, 0.f, 0.f, 0.f};
;         cur = nxt; cA = nA; cB = nB; ++ui;
;         if (wr == 1) PG8_BAR;
	v_pk_fma_f32 v[42:43], v[42:43], v[50:51], v[94:95]
	v_pk_fma_f32 v[40:41], v[40:41], v[48:49], v[92:93]
	global_store_dwordx4 v[52:53], v[40:43], off
	s_nop 1
	v_mov_b32_e32 v40, v232
	v_mov_b32_e32 v41, v233
	v_mov_b32_e32 v42, v231
	v_mov_b32_e32 v43, v237
	v_add_u32_e32 v48, s15, v171
	v_ashrrev_i32_e32 v49, 31, v48
	v_lshlrev_b64 v[48:49], 13, v[48:49]
	v_lshl_add_u64 v[48:49], s[4:5], 0, v[48:49]
	v_lshl_add_u64 v[48:49], v[48:49], 0, v[158:159]
	s_add_i32 s15, s13, 0xa0
	s_addk_i32 s13, 0xb0
	s_waitcnt lgkmcnt(0)
	v_pk_fma_f32 v[42:43], v[46:47], v[42:43], v[102:103]
	v_pk_fma_f32 v[40:41], v[44:45], v[40:41], v[100:101]
	global_store_dwordx4 v[48:49], v[40:43], off
	s_nop 1
	v_mov_b32_e32 v40, v248
	v_mov_b32_e32 v41, v249
	v_mov_b32_e32 v42, v247
	v_mov_b32_e32 v43, v238
	ds_write_b128 v168, v[36:39]
	ds_write_b128 v169, v[32:35]
	ds_read_b128 v[32:35], v161
	ds_read_b128 v[36:39], v170
	s_waitcnt lgkmcnt(1)
	v_pk_fma_f32 v[34:35], v[34:35], v[42:43], v[98:99]
	v_pk_fma_f32 v[32:33], v[32:33], v[40:41], v[96:97]
	global_store_dwordx4 v[52:53], v[32:35], off offset:128
	s_nop 1
	v_mov_b32_e32 v32, v248
	v_mov_b32_e32 v33, v249
	v_mov_b32_e32 v34, v247
	v_mov_b32_e32 v35, v238
	s_waitcnt lgkmcnt(0)
	v_pk_fma_f32 v[34:35], v[38:39], v[34:35], v[106:107]
	v_pk_fma_f32 v[32:33], v[36:37], v[32:33], v[104:105]
	global_store_dwordx4 v[48:49], v[32:35], off offset:128
	s_nop 1
	v_mov_b32_e32 v32, v232
	v_mov_b32_e32 v33, v233
	v_mov_b32_e32 v34, v231
	v_mov_b32_e32 v35, v237
	ds_write_b128 v168, v[28:31]
	ds_write_b128 v169, v[24:27]
	ds_read_b128 v[24:27], v161
	v_add_u32_e32 v36, s15, v167
	v_ashrrev_i32_e32 v37, 31, v36
	v_lshlrev_b64 v[28:29], 13, v[36:37]
	v_lshl_add_u64 v[28:29], s[4:5], 0, v[28:29]
	v_lshl_add_u64 v[36:37], v[28:29], 0, v[158:159]
	ds_read_b128 v[28:31], v170
	s_waitcnt lgkmcnt(1)
	v_pk_fma_f32 v[26:27], v[26:27], v[34:35], v[110:111]
	v_pk_fma_f32 v[24:25], v[24:25], v[32:33], v[108:109]
	global_store_dwordx4 v[36:37], v[24:27], off
	s_nop 1
	v_mov_b32_e32 v24, v232
	v_mov_b32_e32 v25, v233
	v_mov_b32_e32 v26, v231
	v_mov_b32_e32 v27, v237
	v_add_u32_e32 v32, s15, v171
	v_ashrrev_i32_e32 v33, 31, v32
	v_lshlrev_b64 v[32:33], 13, v[32:33]
	v_lshl_add_u64 v[32:33], s[4:5], 0, v[32:33]
	v_lshl_add_u64 v[32:33], v[32:33], 0, v[158:159]
	s_waitcnt lgkmcnt(0)
	v_pk_fma_f32 v[26:27], v[30:31], v[26:27], v[118:119]
	v_pk_fma_f32 v[24:25], v[28:29], v[24:25], v[116:117]
	global_store_dwordx4 v[32:33], v[24:27], off
	s_nop 1
	v_mov_b32_e32 v24, v248
	v_mov_b32_e32 v25, v249
	v_mov_b32_e32 v26, v247
	v_mov_b32_e32 v27, v238
	ds_write_b128 v168, v[20:23]
	ds_write_b128 v169, v[16:19]
	ds_read_b128 v[16:19], v161
	ds_read_b128 v[20:23], v170
	s_waitcnt lgkmcnt(1)
	v_pk_fma_f32 v[18:19], v[18:19], v[26:27], v[114:115]
	v_pk_fma_f32 v[16:17], v[16:17], v[24:25], v[112:113]
	global_store_dwordx4 v[36:37], v[16:19], off offset:128
	s_nop 1
	v_mov_b32_e32 v16, v248
	v_mov_b32_e32 v17, v249
	v_mov_b32_e32 v18, v247
	v_mov_b32_e32 v19, v238
	s_waitcnt lgkmcnt(0)
	v_pk_fma_f32 v[18:19], v[22:23], v[18:19], v[122:123]
	v_pk_fma_f32 v[16:17], v[20:21], v[16:17], v[120:121]
	global_store_dwordx4 v[32:33], v[16:19], off offset:128
	s_nop 1
	v_mov_b32_e32 v16, v232
	v_mov_b32_e32 v17, v233
	v_mov_b32_e32 v18, v231
	v_mov_b32_e32 v19, v237
	ds_write_b128 v168, v[12:15]
	ds_write_b128 v169, v[8:11]
	ds_read_b128 v[8:11], v161
	v_add_u32_e32 v20, s13, v167
	v_ashrrev_i32_e32 v21, 31, v20
	v_lshlrev_b64 v[12:13], 13, v[20:21]
	v_lshl_add_u64 v[12:13], s[4:5], 0, v[12:13]
	v_lshl_add_u64 v[20:21], v[12:13], 0, v[158:159]
	ds_read_b128 v[12:15], v170
	s_waitcnt lgkmcnt(1)
	v_pk_fma_f32 v[10:11], v[10:11], v[18:19], v[70:71]
	v_pk_fma_f32 v[8:9], v[8:9], v[16:17], v[68:69]
	global_store_dwordx4 v[20:21], v[8:11], off
	s_nop 1
	v_mov_b32_e32 v8, v232
	v_mov_b32_e32 v9, v233
	v_mov_b32_e32 v10, v231
	v_mov_b32_e32 v11, v237
	v_add_u32_e32 v16, s13, v171
	v_ashrrev_i32_e32 v17, 31, v16
	v_lshlrev_b64 v[16:17], 13, v[16:17]
	v_lshl_add_u64 v[16:17], s[4:5], 0, v[16:17]
	v_lshl_add_u64 v[16:17], v[16:17], 0, v[158:159]
	s_waitcnt lgkmcnt(0)
	v_pk_fma_f32 v[10:11], v[14:15], v[10:11], v[66:67]
	v_pk_fma_f32 v[8:9], v[12:13], v[8:9], v[64:65]
	global_store_dwordx4 v[16:17], v[8:11], off
	s_nop 1
	v_mov_b32_e32 v8, v248
	v_mov_b32_e32 v9, v249
	v_mov_b32_e32 v10, v247
	v_mov_b32_e32 v11, v238
	ds_write_b128 v168, v[4:7]
	ds_write_b128 v169, v[0:3]
	ds_read_b128 v[0:3], v161
	ds_read_b128 v[4:7], v170
	s_waitcnt lgkmcnt(1)
	v_pk_fma_f32 v[2:3], v[2:3], v[10:11], v[62:63]
	v_pk_fma_f32 v[0:1], v[0:1], v[8:9], v[60:61]
	global_store_dwordx4 v[20:21], v[0:3], off offset:128
	s_nop 1
	v_mov_b32_e32 v0, v248
	v_mov_b32_e32 v1, v249
	v_mov_b32_e32 v2, v247
	v_mov_b32_e32 v3, v238
	s_waitcnt lgkmcnt(0)
	v_pk_fma_f32 v[2:3], v[6:7], v[2:3], v[58:59]
	v_pk_fma_f32 v[0:1], v[4:5], v[0:1], v[56:57]
	global_store_dwordx4 v[16:17], v[0:3], off offset:128
	s_cbranch_vccnz .LBB0_592
	s_andn2_b64 vcc, exec, s[10:11]
	s_cbranch_vccnz .LBB0_591
	s_barrier
	s_branch .LBB0_591
